# SSD y_inter: all 20 LDS reads issued up front with counted lgkmcnt waits (same accumulation order); conv_ffn: removed phantom vmcnt waits between job loads
# baseline (speedup 1.0000x reference)
.LBB0_1040:
	s_xor_b64 s[24:25], s[22:23], -1
	s_xor_b64 s[22:23], s[78:79], -1
	s_add_i32 s47, s47, 1
	s_cmp_eq_u32 s35, 0
	s_cselect_b64 s[78:79], -1, 0
	s_andn2_b64 vcc, exec, s[24:25]
	s_mov_b64 s[24:25], -1
	s_cbranch_vccnz .LBB0_1113
	s_and_b64 s[24:25], s[78:79], exec
	s_mov_b32 s24, 0x1e400
	s_cselect_b32 s24, 0x1a000, s24
	v_add_u32_e32 v94, s24, v149
	s_waitcnt vmcnt(2)
	ds_read_b128 v[98:101], v161
	ds_read_b128 v[66:69], v94
	ds_read_b128 v[70:73], v94 offset:4352
	ds_read_b128 v[74:77], v94 offset:8704
	ds_read_b128 v[78:81], v94 offset:13056
	ds_read_b128 v[102:105], v161 offset:64
	ds_read_b128 v[82:85], v94 offset:64
	ds_read_b128 v[86:89], v94 offset:4416
	ds_read_b128 v[90:93], v94 offset:8768
	ds_read_b128 v[168:171], v94 offset:13120
	ds_read_b128 v[106:109], v161 offset:128
	ds_read_b128 v[172:175], v94 offset:128
	ds_read_b128 v[176:179], v94 offset:4480
	ds_read_b128 v[180:183], v94 offset:8832
	ds_read_b128 v[184:187], v94 offset:13184
	s_andn2_b64 vcc, exec, s[62:63]
	s_waitcnt lgkmcnt(13)
	v_mfma_f32_16x16x32_bf16 v[204:207], v[66:69], v[98:101], 0
	ds_read_b128 v[110:113], v161 offset:192
	s_waitcnt lgkmcnt(13)
	v_mfma_f32_16x16x32_bf16 v[208:211], v[70:73], v[98:101], 0
	ds_read_b128 v[188:191], v94 offset:192
	s_waitcnt lgkmcnt(13)
	v_mfma_f32_16x16x32_bf16 v[212:215], v[74:77], v[98:101], 0
	ds_read_b128 v[192:195], v94 offset:4544
	s_waitcnt lgkmcnt(13)
	v_mfma_f32_16x16x32_bf16 v[216:219], v[78:81], v[98:101], 0
	ds_read_b128 v[196:199], v94 offset:8896
	s_waitcnt lgkmcnt(12)
	v_mfma_f32_16x16x32_bf16 v[204:207], v[82:85], v[102:105], v[204:207]
	ds_read_b128 v[200:203], v94 offset:13248
	s_waitcnt lgkmcnt(12)
	v_mfma_f32_16x16x32_bf16 v[208:211], v[86:89], v[102:105], v[208:211]
	s_waitcnt lgkmcnt(11)
	v_mfma_f32_16x16x32_bf16 v[212:215], v[90:93], v[102:105], v[212:215]
	s_waitcnt lgkmcnt(10)
	v_mfma_f32_16x16x32_bf16 v[216:219], v[168:171], v[102:105], v[216:219]
	s_waitcnt lgkmcnt(8)
	v_mfma_f32_16x16x32_bf16 v[204:207], v[172:175], v[106:109], v[204:207]
	s_waitcnt lgkmcnt(7)
	v_mfma_f32_16x16x32_bf16 v[208:211], v[176:179], v[106:109], v[208:211]
	s_waitcnt lgkmcnt(6)
	v_mfma_f32_16x16x32_bf16 v[212:215], v[180:183], v[106:109], v[212:215]
	s_waitcnt lgkmcnt(5)
	v_mfma_f32_16x16x32_bf16 v[216:219], v[184:187], v[106:109], v[216:219]
	s_waitcnt lgkmcnt(3)
	v_mfma_f32_16x16x32_bf16 v[66:69], v[188:191], v[110:113], v[204:207]
	s_waitcnt lgkmcnt(2)
	v_mfma_f32_16x16x32_bf16 v[70:73], v[192:195], v[110:113], v[208:211]
	s_waitcnt lgkmcnt(1)
	v_mfma_f32_16x16x32_bf16 v[78:81], v[196:199], v[110:113], v[212:215]
	s_waitcnt lgkmcnt(0)
	v_mfma_f32_16x16x32_bf16 v[74:77], v[200:203], v[110:113], v[216:219]
	s_cbranch_vccnz .LBB0_1043
	s_and_b64 s[24:25], s[92:93], exec
	s_cselect_b32 s24, 1, 35
	s_sub_i32 s24, s24, s47
	s_lshl_b32 s25, s24, 7
	s_or_b32 s26, s25, s0
	s_add_i32 s25, s25, s1
	s_cmp_lt_u32 s24, 2
	s_cselect_b32 s24, s26, s25
	v_add_u32_e32 v0, s24, v137
	v_ashrrev_i32_e32 v1, 31, v0
	v_lshlrev_b64 v[0:1], 13, v[0:1]
	v_add_u32_e32 v8, s24, v138
	v_lshl_add_u64 v[0:1], s[44:45], 0, v[0:1]
	s_mov_b32 s83, s67
	v_ashrrev_i32_e32 v9, 31, v8
	v_lshl_add_u64 v[0:1], v[0:1], 0, s[82:83]
	v_lshlrev_b64 v[8:9], 13, v[8:9]
	v_add_u32_e32 v16, s24, v139
	v_lshl_add_u64 v[0:1], v[0:1], 0, v[64:65]
	s_movk_i32 s25, 0x1000
	v_lshl_add_u64 v[8:9], s[44:45], 0, v[8:9]
	v_ashrrev_i32_e32 v17, 31, v16
	v_add_co_u32_e32 v4, vcc, s25, v0
	v_lshl_add_u64 v[8:9], v[8:9], 0, s[82:83]
	v_lshlrev_b64 v[16:17], 13, v[16:17]
	v_add_u32_e32 v24, s24, v140
	v_addc_co_u32_e32 v5, vcc, 0, v1, vcc
	v_lshl_add_u64 v[8:9], v[8:9], 0, v[64:65]
	v_lshl_add_u64 v[16:17], s[44:45], 0, v[16:17]
	v_ashrrev_i32_e32 v25, 31, v24
	v_add_co_u32_e32 v12, vcc, s25, v8
	v_lshl_add_u64 v[16:17], v[16:17], 0, s[82:83]
	v_lshlrev_b64 v[24:25], 13, v[24:25]
	v_addc_co_u32_e32 v13, vcc, 0, v9, vcc
	v_lshl_add_u64 v[16:17], v[16:17], 0, v[64:65]
	v_lshl_add_u64 v[24:25], s[44:45], 0, v[24:25]
	v_add_co_u32_e32 v20, vcc, s25, v16
	v_lshl_add_u64 v[24:25], v[24:25], 0, s[82:83]
	v_add_u32_e32 v32, s24, v136
	v_addc_co_u32_e32 v21, vcc, 0, v17, vcc
	v_lshl_add_u64 v[24:25], v[24:25], 0, v[64:65]
	v_ashrrev_i32_e32 v33, 31, v32
	v_add_co_u32_e32 v28, vcc, s25, v24
	v_lshlrev_b64 v[32:33], 13, v[32:33]
	s_nop 0
	v_addc_co_u32_e32 v29, vcc, 0, v25, vcc
	v_lshl_add_u64 v[36:37], v[130:131], 0, v[32:33]
	global_load_dwordx4 v[0:3], v[4:5], off offset:2048
	s_nop 0
	global_load_dwordx4 v[4:7], v[4:5], off
	s_nop 0
	global_load_dwordx4 v[8:11], v[12:13], off offset:2048
	s_nop 0
	global_load_dwordx4 v[12:15], v[12:13], off
	s_nop 0
	global_load_dwordx4 v[16:19], v[20:21], off offset:2048
	s_nop 0
	global_load_dwordx4 v[20:23], v[20:21], off
	s_nop 0
	global_load_dwordx4 v[24:27], v[28:29], off offset:2048
	s_nop 0
	global_load_dwordx4 v[28:31], v[28:29], off
	s_nop 0
	global_load_dwordx4 v[32:35], v[36:37], off offset:16
	s_nop 0
	global_load_dwordx4 v[36:39], v[36:37], off
	s_mov_b32 s83, 0x41a00000

.LBB0_1162:
	s_xor_b64 s[24:25], s[22:23], -1
	s_xor_b64 s[36:37], s[36:37], -1
	s_add_i32 s26, s34, 1
	s_cmp_eq_u32 s83, 0
	s_cselect_b64 s[22:23], -1, 0
	s_andn2_b64 vcc, exec, s[24:25]
	s_mov_b64 s[24:25], -1
	s_cbranch_vccnz .LBB0_1235
	s_and_b64 s[24:25], s[22:23], exec
	s_mov_b32 s24, 0x1e400
	s_cselect_b32 s24, 0x1a000, s24
	v_add_u32_e32 v94, s24, v151
	s_waitcnt vmcnt(2)
	ds_read_b128 v[102:105], v161
	ds_read_b128 v[66:69], v94
	ds_read_b128 v[70:73], v94 offset:4352
	ds_read_b128 v[74:77], v94 offset:8704
	ds_read_b128 v[78:81], v94 offset:13056
	ds_read_b128 v[106:109], v161 offset:64
	ds_read_b128 v[82:85], v94 offset:64
	ds_read_b128 v[86:89], v94 offset:4416
	ds_read_b128 v[90:93], v94 offset:8768
	ds_read_b128 v[168:171], v94 offset:13120
	ds_read_b128 v[110:113], v161 offset:128
	ds_read_b128 v[172:175], v94 offset:128
	ds_read_b128 v[176:179], v94 offset:4480
	ds_read_b128 v[180:183], v94 offset:8832
	ds_read_b128 v[184:187], v94 offset:13184
	s_andn2_b64 vcc, exec, s[20:21]
	s_waitcnt lgkmcnt(13)
	v_mfma_f32_16x16x32_bf16 v[204:207], v[66:69], v[102:105], 0
	ds_read_b128 v[126:129], v161 offset:192
	s_waitcnt lgkmcnt(13)
	v_mfma_f32_16x16x32_bf16 v[208:211], v[70:73], v[102:105], 0
	ds_read_b128 v[188:191], v94 offset:192
	s_waitcnt lgkmcnt(13)
	v_mfma_f32_16x16x32_bf16 v[212:215], v[74:77], v[102:105], 0
	ds_read_b128 v[192:195], v94 offset:4544
	s_waitcnt lgkmcnt(13)
	v_mfma_f32_16x16x32_bf16 v[216:219], v[78:81], v[102:105], 0
	ds_read_b128 v[196:199], v94 offset:8896
	s_waitcnt lgkmcnt(12)
	v_mfma_f32_16x16x32_bf16 v[204:207], v[82:85], v[106:109], v[204:207]
	ds_read_b128 v[200:203], v94 offset:13248
	s_waitcnt lgkmcnt(12)
	v_mfma_f32_16x16x32_bf16 v[208:211], v[86:89], v[106:109], v[208:211]
	s_waitcnt lgkmcnt(11)
	v_mfma_f32_16x16x32_bf16 v[212:215], v[90:93], v[106:109], v[212:215]
	s_waitcnt lgkmcnt(10)
	v_mfma_f32_16x16x32_bf16 v[216:219], v[168:171], v[106:109], v[216:219]
	s_waitcnt lgkmcnt(8)
	v_mfma_f32_16x16x32_bf16 v[204:207], v[172:175], v[110:113], v[204:207]
	s_waitcnt lgkmcnt(7)
	v_mfma_f32_16x16x32_bf16 v[208:211], v[176:179], v[110:113], v[208:211]
	s_waitcnt lgkmcnt(6)
	v_mfma_f32_16x16x32_bf16 v[212:215], v[180:183], v[110:113], v[212:215]
	s_waitcnt lgkmcnt(5)
	v_mfma_f32_16x16x32_bf16 v[216:219], v[184:187], v[110:113], v[216:219]
	s_waitcnt lgkmcnt(3)
	v_mfma_f32_16x16x32_bf16 v[78:81], v[188:191], v[126:129], v[204:207]
	s_waitcnt lgkmcnt(2)
	v_mfma_f32_16x16x32_bf16 v[74:77], v[192:195], v[126:129], v[208:211]
	s_waitcnt lgkmcnt(1)
	v_mfma_f32_16x16x32_bf16 v[70:73], v[196:199], v[126:129], v[212:215]
	s_waitcnt lgkmcnt(0)
	v_mfma_f32_16x16x32_bf16 v[66:69], v[200:203], v[126:129], v[216:219]
	s_cbranch_vccnz .LBB0_1165
	s_lshl_b32 s24, s26, 7
	s_and_b64 s[20:21], s[56:57], exec
	s_movk_i32 s21, 0xff00
	s_cselect_b32 s20, 8, 12
	s_cselect_b32 s21, 0x4000, s21
	s_lshl_b32 s20, s31, s20
	s_add_i32 s21, s24, s21
	s_add_i32 s21, s21, s20
	v_add_u32_e32 v0, s21, v139
	v_ashrrev_i32_e32 v1, 31, v0
	v_lshlrev_b64 v[0:1], 13, v[0:1]
	v_add_u32_e32 v8, s21, v140
	v_lshl_add_u64 v[0:1], s[44:45], 0, v[0:1]
	s_mov_b32 s83, s67
	v_ashrrev_i32_e32 v9, 31, v8
	v_lshl_add_u64 v[0:1], v[0:1], 0, s[82:83]
	v_lshlrev_b64 v[8:9], 13, v[8:9]
	v_add_u32_e32 v16, s21, v141
	v_lshl_add_u64 v[0:1], v[0:1], 0, v[64:65]
	s_movk_i32 s20, 0x1000
	v_lshl_add_u64 v[8:9], s[44:45], 0, v[8:9]
	v_ashrrev_i32_e32 v17, 31, v16
	v_add_co_u32_e32 v4, vcc, s20, v0
	v_lshl_add_u64 v[8:9], v[8:9], 0, s[82:83]
	v_lshlrev_b64 v[16:17], 13, v[16:17]
	v_add_u32_e32 v24, s21, v142
	v_addc_co_u32_e32 v5, vcc, 0, v1, vcc
	v_lshl_add_u64 v[8:9], v[8:9], 0, v[64:65]
	v_lshl_add_u64 v[16:17], s[44:45], 0, v[16:17]
	v_ashrrev_i32_e32 v25, 31, v24
	v_add_co_u32_e32 v12, vcc, s20, v8
	v_lshl_add_u64 v[16:17], v[16:17], 0, s[82:83]
	v_lshlrev_b64 v[24:25], 13, v[24:25]
	v_addc_co_u32_e32 v13, vcc, 0, v9, vcc
	v_lshl_add_u64 v[16:17], v[16:17], 0, v[64:65]
	v_lshl_add_u64 v[24:25], s[44:45], 0, v[24:25]
	v_add_co_u32_e32 v20, vcc, s20, v16
	v_lshl_add_u64 v[24:25], v[24:25], 0, s[82:83]
	v_add_u32_e32 v32, s21, v138
	v_addc_co_u32_e32 v21, vcc, 0, v17, vcc
	v_lshl_add_u64 v[24:25], v[24:25], 0, v[64:65]
	v_ashrrev_i32_e32 v33, 31, v32
	v_add_co_u32_e32 v28, vcc, s20, v24
	v_lshlrev_b64 v[32:33], 13, v[32:33]
	s_nop 0
	v_addc_co_u32_e32 v29, vcc, 0, v25, vcc
	v_lshl_add_u64 v[36:37], v[132:133], 0, v[32:33]
	global_load_dwordx4 v[0:3], v[4:5], off offset:2048
	s_nop 0
	global_load_dwordx4 v[4:7], v[4:5], off
	s_nop 0
	global_load_dwordx4 v[8:11], v[12:13], off offset:2048
	s_nop 0
	global_load_dwordx4 v[12:15], v[12:13], off
	s_nop 0
	global_load_dwordx4 v[16:19], v[20:21], off offset:2048
	s_nop 0
	global_load_dwordx4 v[20:23], v[20:21], off
	s_nop 0
	global_load_dwordx4 v[24:27], v[28:29], off offset:2048
	s_nop 0
	global_load_dwordx4 v[28:31], v[28:29], off
	s_nop 0
	global_load_dwordx4 v[32:35], v[36:37], off offset:16
	s_nop 0
	global_load_dwordx4 v[36:39], v[36:37], off

.LBB0_2191:
	s_lshr_b32 s25, s41, 5
	v_cvt_f32_ubyte0_e32 v0, s25
	v_rcp_iflag_f32_e32 v0, v0
	s_sub_i32 s34, 0, s25
	s_abs_i32 s29, s40
	s_ashr_i32 s28, s40, 31
	v_mul_f32_e32 v0, 0x4f7ffffe, v0
	v_cvt_u32_f32_e32 v0, v0
	v_mov_b32_e32 v4, 0
	v_mov_b32_e32 v5, 0
	v_mov_b32_e32 v6, 0
	v_readfirstlane_b32 s35, v0
	s_mul_i32 s34, s34, s35
	s_mul_hi_u32 s34, s35, s34
	s_add_i32 s35, s35, s34
	s_mul_hi_u32 s34, s29, s35
	s_mul_i32 s35, s34, s25
	s_sub_i32 s29, s29, s35
	s_add_i32 s43, s34, 1
	s_sub_i32 s35, s29, s25
	s_cmp_ge_u32 s29, s25
	s_cselect_b32 s34, s43, s34
	s_cselect_b32 s29, s35, s29
	s_add_i32 s35, s34, 1
	s_cmp_ge_u32 s29, s25
	s_cselect_b32 s29, s35, s34
	s_xor_b32 s29, s29, s28
	s_sub_i32 s28, s29, s28
	s_mul_i32 s25, s28, s25
	s_sub_i32 s25, s40, s25
	s_lshl_b32 s29, s25, 4
	s_and_b32 s29, s29, 0xffffff80
	v_and_or_b32 v1, s25, 4, v104
	v_lshl_or_b32 v0, s25, 5, v103
	v_add_u32_e32 v1, s29, v1
	v_and_or_b32 v1, v0, s49, v1
	v_cndmask_b32_e64 v64, v0, v1, s[6:7]
	v_cmp_lt_i32_e32 vcc, -1, v64
	v_lshl_or_b32 v99, s28, 6, v102
	v_mov_b32_e32 v0, 0
	v_lshlrev_b64 v[100:101], 2, v[64:65]
	v_mov_b32_e32 v7, 0
	s_nop 0
	v_mov_b32_e32 v8, 0
	v_mov_b32_e32 v9, 0
	v_mov_b32_e32 v10, 0
	v_mov_b32_e32 v11, 0
	s_and_saveexec_b64 s[6:7], vcc
	s_cbranch_execz .LBB0_2193
	v_or_b32_e32 v1, 8, v99
	v_mad_i64_i32 v[2:3], s[28:29], s24, v99, 0
	v_mad_i64_i32 v[4:5], s[28:29], s24, v1, 0
	v_lshl_add_u64 v[2:3], v[2:3], 2, s[20:21]
	v_lshl_add_u64 v[4:5], v[4:5], 2, s[20:21]
	v_lshl_add_u64 v[2:3], v[2:3], 0, v[100:101]
	v_lshl_add_u64 v[8:9], v[4:5], 0, v[100:101]
	global_load_dwordx4 v[4:7], v[2:3], off
	s_nop 0
	global_load_dwordx4 v[8:11], v[8:9], off

.LBB0_2195:
	s_or_b64 exec, exec, s[6:7]
	s_nop 0
	v_mov_b32_e32 v31, 0
	v_mov_b32_e32 v36, 0
	v_mov_b32_e32 v37, 0
	v_mov_b32_e32 v38, 0
	v_mov_b32_e32 v39, 0
	v_mov_b32_e32 v40, 0
	v_mov_b32_e32 v41, 0
	v_mov_b32_e32 v42, 0
	v_mov_b32_e32 v43, 0
	s_and_saveexec_b64 s[6:7], vcc
	s_cbranch_execz .LBB0_2197
	v_or_b32_e32 v28, 32, v99
	v_or_b32_e32 v30, 40, v99
	v_mad_i64_i32 v[28:29], s[28:29], s24, v28, 0
	v_mad_i64_i32 v[36:37], s[28:29], s24, v30, 0
	v_lshl_add_u64 v[28:29], v[28:29], 2, s[20:21]
	v_lshl_add_u64 v[36:37], v[36:37], 2, s[20:21]
	v_lshl_add_u64 v[28:29], v[28:29], 0, v[100:101]
	v_lshl_add_u64 v[40:41], v[36:37], 0, v[100:101]
	global_load_dwordx4 v[36:39], v[28:29], off
	s_nop 0
	global_load_dwordx4 v[40:43], v[40:41], off

.LBB0_2207:
	s_lshr_b32 s19, s36, 5
	s_nop 0
	v_cvt_f32_ubyte0_e32 v12, s19
	v_rcp_iflag_f32_e32 v12, v12
	s_sub_i32 s45, 0, s19
	s_abs_i32 s44, s27
	s_ashr_i32 s43, s27, 31
	v_mul_f32_e32 v12, 0x4f7ffffe, v12
	v_cvt_u32_f32_e32 v12, v12
	v_mov_b32_e32 v16, 0
	v_mov_b32_e32 v14, 0
	v_mov_b32_e32 v15, 0
	v_readfirstlane_b32 s47, v12
	s_mul_i32 s45, s45, s47
	s_mul_hi_u32 s45, s47, s45
	s_add_i32 s47, s47, s45
	s_mul_hi_u32 s45, s44, s47
	s_mul_i32 s47, s45, s19
	s_sub_i32 s44, s44, s47
	s_add_i32 s48, s45, 1
	s_sub_i32 s47, s44, s19
	s_cmp_ge_u32 s44, s19
	s_cselect_b32 s45, s48, s45
	s_cselect_b32 s44, s47, s44
	s_add_i32 s47, s45, 1
	s_cmp_ge_u32 s44, s19
	s_cselect_b32 s44, s47, s45
	s_xor_b32 s44, s44, s43
	s_sub_i32 s43, s44, s43
	s_mul_i32 s19, s43, s19
	s_sub_i32 s19, s27, s19
	s_lshl_b32 s44, s19, 4
	s_and_b32 s44, s44, 0xffffff80
	v_and_or_b32 v13, s19, 4, v104
	v_lshl_or_b32 v12, s19, 5, v103
	v_add_u32_e32 v13, s44, v13
	v_and_or_b32 v13, v12, s49, v13
	v_cndmask_b32_e64 v64, v12, v13, s[6:7]
	v_cmp_lt_i32_e32 vcc, -1, v64
	v_lshl_or_b32 v99, s43, 6, v102
	v_lshlrev_b64 v[100:101], 2, v[64:65]
	v_mov_b32_e32 v12, 0
	v_mov_b32_e32 v13, 0
	v_mov_b32_e32 v20, 0
	v_mov_b32_e32 v21, 0
	v_mov_b32_e32 v22, 0
	v_mov_b32_e32 v23, 0
	s_and_saveexec_b64 s[6:7], vcc
	s_cbranch_execz .LBB0_2209
	v_mad_i64_i32 v[12:13], s[44:45], s34, v99, 0
	v_or_b32_e32 v14, 8, v99
	v_lshl_add_u64 v[12:13], v[12:13], 2, s[28:29]
	v_mad_i64_i32 v[14:15], s[44:45], s34, v14, 0
	v_lshl_add_u64 v[12:13], v[12:13], 0, v[100:101]
	v_lshl_add_u64 v[14:15], v[14:15], 2, s[28:29]
	v_lshl_add_u64 v[18:19], v[14:15], 0, v[100:101]
	global_load_dwordx4 v[12:15], v[12:13], off
	s_nop 0
	global_load_dwordx4 v[20:23], v[18:19], off
